# grid barrier between mix (scan+attention) and GLA-output phase replaced by finished-scan-item counter (per-item wbl2+atomic, leader spin + inv): glaout overlaps other WGs attention tail
# speedup vs baseline: 1.0075x; 1.0017x over previous
; __device__ __forceinline__ unsigned xb_xcc_id() { return (unsigned)__builtin_amdgcn_s_getreg((3 << 11) | 20) & 0xFu; }
; __device__ __forceinline__ void gla_scan_item(ArgsP a, int item, LAS unsigned char* lds) {
;     ...
;     }
;     ...
;     __syncthreads();
; }
; __device__ __forceinline__ void ph_mix(int l, LAS unsigned char* lds, unsigned char* lds_raw) {
;     ...
;     for (;;) {
;         PH_PRE
;         const int x0 = (int)(xb_xcc_id() & 7u);
;         unsigned* qbase = (unsigned*)(ws + WS_CTL) + CW_Q + 64 * (l * 8);
;         if (tid == 0) { int found = -1;
;             for (int dx = 0; dx < 8; ++dx) { const int y = (x0 + dx) & 7; unsigned* qp = qbase + 64 * y;
;                 if (__hip_atomic_load(qp, __ATOMIC_RELAXED, __HIP_MEMORY_SCOPE_AGENT) >= (unsigned)nq) continue;
;                 const int idx = (int)__hip_atomic_fetch_add(qp, 1u, __ATOMIC_RELAXED, __HIP_MEMORY_SCOPE_AGENT);
;                 if (idx < nq) { found = y * 256 + idx; break; } }
;             *s_item = found; }
;         __syncthreads(); const int itq = __builtin_amdgcn_readfirstlane(*s_item); __syncthreads();
.LBB0_1310:
	s_waitcnt vmcnt(0)
	s_barrier
	v_cmp_eq_u32_e32 vcc, 0, v206
	s_and_saveexec_b64 s[2:3], vcc
	s_cbranch_execz .Lmy_sd_skip
	s_load_dwordx2 s[4:5], s[0:1], 0xd0
	v_readlane_b32 s10, v255, 8
	buffer_wbl2 sc1
	v_mov_b32_e32 v0, 0
	v_mov_b32_e32 v1, 1
	s_lshl_b32 s10, s10, 8
	s_waitcnt vmcnt(0) lgkmcnt(0)
	s_add_u32 s4, s4, s10
	s_addc_u32 s5, s5, 0
	s_add_u32 s4, s4, 0x1500
	s_addc_u32 s5, s5, 0
	global_atomic_add v0, v1, s[4:5]
.Lmy_sd_skip:
	s_or_b64 exec, exec, s[2:3]
.LBB0_1311:
.LBB0_1312:
	s_mov_b64 s[2:3], s[0:1]
	s_waitcnt vmcnt(0)
	v_mov_b32_e32 v0, v206
	s_mov_b32 s4, s8
	s_load_dwordx2 s[68:69], s[2:3], 0xd0
	s_getreg_b32 s10, hwreg(HW_REG_XCC_ID, 0, 4)
	v_cmp_eq_u32_e32 vcc, 0, v0
	s_and_saveexec_b64 s[2:3], vcc
	s_cbranch_execz .LBB0_1373
	s_waitcnt lgkmcnt(0)
	s_add_u32 s4, s68, s6
	s_addc_u32 s5, s69, s7
	s_and_b32 s24, s10, 7
	s_lshl_b32 s12, s24, 8
	v_mov_b32_e32 v0, s12
	global_load_dword v0, v0, s[4:5] offset:256 sc1
	s_add_u32 s12, s4, s12
	s_addc_u32 s13, s5, 0
	s_waitcnt vmcnt(0)
	v_cmp_le_u32_e32 vcc, s31, v0
	s_cbranch_vccnz .LBB0_1317
	s_mov_b64 s[16:17], exec
	v_mbcnt_lo_u32_b32 v0, s16, 0
	v_mbcnt_hi_u32_b32 v0, s17, v0
	v_cmp_eq_u32_e32 vcc, 0, v0
	s_and_saveexec_b64 s[14:15], vcc
	s_cbranch_execz .LBB0_1316
	s_bcnt1_i32_b64 s16, s[16:17]
	v_mov_b32_e32 v1, s16
	global_atomic_add v1, v161, v1, s[12:13] offset:256 sc0

; #define LAS __attribute__((address_space(3)))
; __device__ __forceinline__ int get_tid() { int t = __builtin_amdgcn_workitem_id_x(); asm volatile("" : "+v"(t)); return t; }
; __device__ __forceinline__ unsigned xb_ld(unsigned* p)              { return __hip_atomic_load(p, __ATOMIC_RELAXED, __HIP_MEMORY_SCOPE_AGENT); }
; __device__ __forceinline__ unsigned xb_add(unsigned* p, unsigned v) { return __hip_atomic_fetch_add(p, v, __ATOMIC_RELAXED, __HIP_MEMORY_SCOPE_AGENT); }
; __device__ __forceinline__ unsigned xb_xcc_id() { return (unsigned)__builtin_amdgcn_s_getreg((3 << 11) | 20) & 0xFu; }
; #define XB_SPIN(cond, bar) do { unsigned _sp = 0; while (cond) { __builtin_amdgcn_s_sleep(1); \
;     if ((++_sp & 255u) == 0u) { if (xb_ld(&(bar)[XB_TMO])) break; if (_sp > XB_SPIN_CAP) { atomicAdd(&(bar)[XB_TMO], 1u); break; } } } } while (0)
; __device__ __forceinline__ void xcd_barrier(unsigned* bar, volatile LAS unsigned* st) {
;     asm volatile("s_waitcnt vmcnt(0)" ::: "memory");
;     __syncthreads();
;     if (get_tid() == 0) {
;         const unsigned x = xb_xcc_id();
;         __builtin_amdgcn_s_waitcnt(0);
;         unsigned nloc = st[0], nx = st[1];
;         if (nloc == 0u) { xcd_barrier_complete(bar, x, nloc, nx); st[0] = nloc; st[1] = nx; }
;         const unsigned old = xb_add(&bar[XB_XSUB(x)], 1u);
;         const unsigned gen = old / nloc;
;         if (old + 1u == (gen + 1u) * nloc) {
;             __builtin_amdgcn_fence(__ATOMIC_RELEASE, "agent");
;             asm volatile("s_waitcnt vmcnt(0)" ::: "memory");
;             const unsigned og = xb_add(&bar[XB_TOP], 1u);
;             const unsigned tg = og / nx;
;             if (og + 1u == (tg + 1u) * nx) xb_add(&bar[XB_TOPGEN], 1u);
;             else XB_SPIN(xb_ld(&bar[XB_TOPGEN]) == tg, bar);
;             __builtin_amdgcn_fence(__ATOMIC_ACQUIRE, "agent");
;             xb_add(&bar[XB_XGEN(x)], 1u);
;             asm volatile("s_waitcnt vmcnt(0)" ::: "memory");
;         } else {
;             XB_SPIN(xb_ld(&bar[XB_XGEN(x)]) == gen, bar);
;             __builtin_amdgcn_fence(__ATOMIC_ACQUIRE, "agent");
;             asm volatile("s_waitcnt vmcnt(0)" ::: "memory");
;         }
;     }
;     __syncthreads();
; }
; __global__ void __launch_bounds__(512, 2) mega(Args a_unused) {
;     ...
;         if (IN(pb + 3)) ph_mix(l, lds, lds_raw);
;         SEAM(pb + 3);
;         if (IN(pb + 4)) ph_glaout(l);
.LBB0_1414:
	s_mov_b64 s[4:5], s[0:1]
	s_load_dword s2, s[4:5], 0xd8
	s_add_i32 s31, s87, 5
	s_waitcnt lgkmcnt(0)
	s_cmp_gt_i32 s2, s54
	s_cbranch_scc1 .LBB0_1469
	s_load_dword s2, s[4:5], 0xdc
	s_waitcnt lgkmcnt(0)
	s_cmp_ge_i32 s31, s2
	s_cbranch_scc1 .LBB0_1469
	s_waitcnt vmcnt(0)
	s_waitcnt vmcnt(0)
	v_mov_b32_e32 v0, v206
	s_barrier
	s_nop 0
	v_cmp_eq_u32_e32 vcc, 0, v0
	s_and_saveexec_b64 s[2:3], vcc
	s_cbranch_execz .LBB0_1468
	s_load_dwordx2 s[4:5], s[4:5], 0xd0
	v_readlane_b32 s6, v255, 8
	v_mov_b32_e32 v0, 0
	s_nop 0
	s_lshl_b32 s6, s6, 8
	s_waitcnt lgkmcnt(0)
	s_add_u32 s4, s4, s6
	s_addc_u32 s5, s5, 0
	s_add_u32 s4, s4, 0x1500
	s_addc_u32 s5, s5, 0
	s_mov_b32 s6, 0
.Lmy_sw_spin:
	global_load_dword v1, v0, s[4:5] sc1
	s_waitcnt vmcnt(0)
	v_readfirstlane_b32 s7, v1
	s_cmpk_ge_u32 s7, 0x80
	s_cbranch_scc1 .Lmy_sw_done
	s_sleep 1
	s_add_i32 s6, s6, 1
	s_cmp_lt_u32 s6, 0x40000
	s_cbranch_scc1 .Lmy_sw_spin
.Lmy_sw_done:
	buffer_inv sc1
	s_waitcnt vmcnt(0)
